# v9 plus last 8 MFMAs of each K step carried across the loop-top barrier and interleaved with the next fragment reads (projection K loops)
# speedup vs baseline: 1.0072x; 1.0072x over previous
.LBB0_130:
	v_add_u32_e32 v164, v168, v189
	v_add_u32_e32 v169, v146, v189
	s_waitcnt lgkmcnt(2)
	v_mfma_f32_32x32x16_bf16 v[0:15], v[128:131], v[132:135], v[0:15]
	ds_read_b128 v[156:159], v164
	s_add_u32 s0, s0, 0x80
	s_addc_u32 s1, s1, 0
	s_add_i32 s47, s47, 1
	s_cmpk_lg_i32 s0, 0x800
	s_mov_b32 s48, s52
	v_mfma_f32_32x32x16_bf16 v[16:31], v[152:155], v[132:135], v[16:31]
	ds_read_b128 v[132:135], v164 offset:4096
	s_waitcnt lgkmcnt(4)
	v_mfma_f32_32x32x16_bf16 v[32:47], v[128:131], v[136:139], v[32:47]
	ds_read_b128 v[160:163], v164 offset:8192
	v_mfma_f32_32x32x16_bf16 v[48:63], v[152:155], v[136:139], v[48:63]
	ds_read_b128 v[136:139], v164 offset:12288
	s_waitcnt lgkmcnt(5)
	v_mfma_f32_32x32x16_bf16 v[64:79], v[128:131], v[140:143], v[64:79]
	ds_read_b128 v[164:167], v169 offset:32768
	v_mfma_f32_32x32x16_bf16 v[80:95], v[152:155], v[140:143], v[80:95]
	ds_read_b128 v[140:143], v169 offset:36864
	v_add_u32_e32 v169, v168, v190
	s_waitcnt lgkmcnt(6)
	v_mfma_f32_32x32x16_bf16 v[96:111], v[128:131], v[148:151], v[96:111]
	v_mfma_f32_32x32x16_bf16 v[112:127], v[152:155], v[148:151], v[112:127]
	s_waitcnt lgkmcnt(1)
	v_mfma_f32_32x32x16_bf16 v[0:15], v[164:167], v[156:159], v[0:15]
	ds_read_b128 v[128:131], v169
	s_waitcnt lgkmcnt(1)
	v_mfma_f32_32x32x16_bf16 v[16:31], v[140:143], v[156:159], v[16:31]
	ds_read_b128 v[148:151], v169 offset:4096
	v_mfma_f32_32x32x16_bf16 v[32:47], v[164:167], v[132:135], v[32:47]
	ds_read_b128 v[152:155], v169 offset:8192
	v_mfma_f32_32x32x16_bf16 v[48:63], v[140:143], v[132:135], v[48:63]
	ds_read_b128 v[132:135], v169 offset:12288
	v_add_u32_e32 v169, v146, v190
	v_add_u32_e32 v146, v146, v191
	v_mfma_f32_32x32x16_bf16 v[64:79], v[164:167], v[160:163], v[64:79]
	ds_read_b128 v[156:159], v169 offset:32768
	v_mfma_f32_32x32x16_bf16 v[80:95], v[140:143], v[160:163], v[80:95]
	ds_read_b128 v[160:163], v169 offset:36864
	v_mfma_f32_32x32x16_bf16 v[96:111], v[164:167], v[136:139], v[96:111]
	v_add_u32_e32 v164, v168, v191
	v_mfma_f32_32x32x16_bf16 v[112:127], v[140:143], v[136:139], v[112:127]
	s_waitcnt lgkmcnt(1)
	v_mfma_f32_32x32x16_bf16 v[0:15], v[156:159], v[128:131], v[0:15]
	ds_read_b128 v[136:139], v164
	s_waitcnt lgkmcnt(1)
	v_mfma_f32_32x32x16_bf16 v[16:31], v[160:163], v[128:131], v[16:31]
	ds_read_b128 v[128:131], v164 offset:4096
	v_mfma_f32_32x32x16_bf16 v[32:47], v[156:159], v[148:151], v[32:47]
	ds_read_b128 v[140:143], v164 offset:8192
	v_mfma_f32_32x32x16_bf16 v[48:63], v[160:163], v[148:151], v[48:63]
	ds_read_b128 v[148:151], v164 offset:12288
	v_mfma_f32_32x32x16_bf16 v[64:79], v[156:159], v[152:155], v[64:79]
	ds_read_b128 v[164:167], v146 offset:32768
	v_mfma_f32_32x32x16_bf16 v[80:95], v[160:163], v[152:155], v[80:95]
	ds_read_b128 v[152:155], v146 offset:36864
	v_mfma_f32_32x32x16_bf16 v[96:111], v[156:159], v[132:135], v[96:111]
	v_mfma_f32_32x32x16_bf16 v[112:127], v[160:163], v[132:135], v[112:127]
	s_waitcnt lgkmcnt(0)
	s_cbranch_scc0 .Lxt_L0
	s_waitcnt vmcnt(0)
	s_barrier
	s_and_b32 s4, s48, 0x10000
	v_or_b32_e32 v146, s4, v187
	v_add_u32_e32 v194, v146, v188
	v_add_u32_e32 v168, s4, v186
	v_add_u32_e32 v195, v168, v188
	ds_read_b128 v[132:135], v195
	v_mfma_f32_32x32x16_bf16 v[16:31], v[152:155], v[136:139], v[16:31]
	v_mfma_f32_32x32x16_bf16 v[48:63], v[152:155], v[128:131], v[48:63]
	v_mfma_f32_32x32x16_bf16 v[80:95], v[152:155], v[140:143], v[80:95]
	v_mfma_f32_32x32x16_bf16 v[112:127], v[152:155], v[148:151], v[112:127]
	ds_read_b128 v[152:155], v194 offset:36864
	v_mfma_f32_32x32x16_bf16 v[0:15], v[164:167], v[136:139], v[0:15]
	ds_read_b128 v[136:139], v195 offset:4096
	v_mfma_f32_32x32x16_bf16 v[32:47], v[164:167], v[128:131], v[32:47]
	ds_read_b128 v[128:131], v194 offset:32768
	v_mfma_f32_32x32x16_bf16 v[64:79], v[164:167], v[140:143], v[64:79]
	ds_read_b128 v[140:143], v195 offset:8192
	v_mfma_f32_32x32x16_bf16 v[96:111], v[164:167], v[148:151], v[96:111]
	ds_read_b128 v[148:151], v195 offset:12288
	s_cmp_lt_u32 s47, 15
	s_mov_b64 s[4:5], -1
	s_cbranch_scc1 .Lft_L0_133
	s_add_i32 s52, s48, 0x10000
	s_mov_b64 s[4:5], 0

.Lxt_L0:
	v_mfma_f32_32x32x16_bf16 v[0:15], v[164:167], v[136:139], v[0:15]
	v_mfma_f32_32x32x16_bf16 v[16:31], v[152:155], v[136:139], v[16:31]
	v_mfma_f32_32x32x16_bf16 v[32:47], v[164:167], v[128:131], v[32:47]
	v_mfma_f32_32x32x16_bf16 v[48:63], v[152:155], v[128:131], v[48:63]
	v_mfma_f32_32x32x16_bf16 v[64:79], v[164:167], v[140:143], v[64:79]
	v_mfma_f32_32x32x16_bf16 v[80:95], v[152:155], v[140:143], v[80:95]
	v_mfma_f32_32x32x16_bf16 v[96:111], v[164:167], v[148:151], v[96:111]
	v_mfma_f32_32x32x16_bf16 v[112:127], v[152:155], v[148:151], v[112:127]
	s_branch .LBB0_135

.Lkin_L0:
	s_and_b32 s4, s48, 0x10000
	v_or_b32_e32 v146, s4, v187
	v_add_u32_e32 v194, v146, v188
	v_add_u32_e32 v168, s4, v186
	v_add_u32_e32 v195, v168, v188
	ds_read_b128 v[132:135], v195
	ds_read_b128 v[152:155], v194 offset:36864
	ds_read_b128 v[136:139], v195 offset:4096
	ds_read_b128 v[128:131], v194 offset:32768
	ds_read_b128 v[140:143], v195 offset:8192
	ds_read_b128 v[148:151], v195 offset:12288
	s_cmp_lt_u32 s47, 15
	s_mov_b64 s[4:5], -1
	s_cbranch_scc1 .LBB0_133
	s_add_i32 s52, s48, 0x10000
	s_mov_b64 s[4:5], 0

.LBB0_725:
	v_add_u32_e32 v162, v166, v189
	v_add_u32_e32 v167, v144, v189
	s_waitcnt lgkmcnt(2)
	v_mfma_f32_32x32x16_bf16 v[0:15], v[128:131], v[132:135], v[0:15]
	ds_read_b128 v[154:157], v162
	s_add_u32 s4, s4, 0x80
	s_addc_u32 s5, s5, 0
	s_add_i32 s45, s45, 1
	s_cmpk_lg_i32 s4, 0x800
	s_mov_b32 s46, s50
	v_mfma_f32_32x32x16_bf16 v[16:31], v[150:153], v[132:135], v[16:31]
	ds_read_b128 v[132:135], v162 offset:4096
	s_waitcnt lgkmcnt(4)
	v_mfma_f32_32x32x16_bf16 v[32:47], v[128:131], v[136:139], v[32:47]
	ds_read_b128 v[158:161], v162 offset:8192
	v_mfma_f32_32x32x16_bf16 v[48:63], v[150:153], v[136:139], v[48:63]
	ds_read_b128 v[136:139], v162 offset:12288
	s_waitcnt lgkmcnt(5)
	v_mfma_f32_32x32x16_bf16 v[64:79], v[128:131], v[140:143], v[64:79]
	ds_read_b128 v[162:165], v167 offset:32768
	v_mfma_f32_32x32x16_bf16 v[80:95], v[150:153], v[140:143], v[80:95]
	ds_read_b128 v[140:143], v167 offset:36864
	v_add_u32_e32 v167, v166, v190
	s_waitcnt lgkmcnt(6)
	v_mfma_f32_32x32x16_bf16 v[96:111], v[128:131], v[146:149], v[96:111]
	v_mfma_f32_32x32x16_bf16 v[112:127], v[150:153], v[146:149], v[112:127]
	s_waitcnt lgkmcnt(1)
	v_mfma_f32_32x32x16_bf16 v[0:15], v[162:165], v[154:157], v[0:15]
	ds_read_b128 v[128:131], v167
	s_waitcnt lgkmcnt(1)
	v_mfma_f32_32x32x16_bf16 v[16:31], v[140:143], v[154:157], v[16:31]
	ds_read_b128 v[146:149], v167 offset:4096
	v_mfma_f32_32x32x16_bf16 v[32:47], v[162:165], v[132:135], v[32:47]
	ds_read_b128 v[150:153], v167 offset:8192
	v_mfma_f32_32x32x16_bf16 v[48:63], v[140:143], v[132:135], v[48:63]
	ds_read_b128 v[132:135], v167 offset:12288
	v_add_u32_e32 v167, v144, v190
	v_add_u32_e32 v144, v144, v191
	v_mfma_f32_32x32x16_bf16 v[64:79], v[162:165], v[158:161], v[64:79]
	ds_read_b128 v[154:157], v167 offset:32768
	v_mfma_f32_32x32x16_bf16 v[80:95], v[140:143], v[158:161], v[80:95]
	ds_read_b128 v[158:161], v167 offset:36864
	v_mfma_f32_32x32x16_bf16 v[96:111], v[162:165], v[136:139], v[96:111]
	v_add_u32_e32 v162, v166, v191
	v_mfma_f32_32x32x16_bf16 v[112:127], v[140:143], v[136:139], v[112:127]
	s_waitcnt lgkmcnt(1)
	v_mfma_f32_32x32x16_bf16 v[0:15], v[154:157], v[128:131], v[0:15]
	ds_read_b128 v[136:139], v162
	s_waitcnt lgkmcnt(1)
	v_mfma_f32_32x32x16_bf16 v[16:31], v[158:161], v[128:131], v[16:31]
	ds_read_b128 v[128:131], v162 offset:4096
	v_mfma_f32_32x32x16_bf16 v[32:47], v[154:157], v[146:149], v[32:47]
	ds_read_b128 v[140:143], v162 offset:8192
	v_mfma_f32_32x32x16_bf16 v[48:63], v[158:161], v[146:149], v[48:63]
	ds_read_b128 v[146:149], v162 offset:12288
	v_mfma_f32_32x32x16_bf16 v[64:79], v[154:157], v[150:153], v[64:79]
	ds_read_b128 v[162:165], v144 offset:32768
	v_mfma_f32_32x32x16_bf16 v[80:95], v[158:161], v[150:153], v[80:95]
	ds_read_b128 v[150:153], v144 offset:36864
	v_mfma_f32_32x32x16_bf16 v[96:111], v[154:157], v[132:135], v[96:111]
	v_mfma_f32_32x32x16_bf16 v[112:127], v[158:161], v[132:135], v[112:127]
	s_waitcnt lgkmcnt(0)
	s_cbranch_scc0 .Lxt_L1
	s_waitcnt vmcnt(0)
	s_barrier
	s_and_b32 s6, s46, 0x10000
	v_or_b32_e32 v144, s6, v187
	v_add_u32_e32 v194, v144, v188
	v_add_u32_e32 v166, s6, v186
	v_add_u32_e32 v195, v166, v188
	ds_read_b128 v[132:135], v195
	v_mfma_f32_32x32x16_bf16 v[16:31], v[150:153], v[136:139], v[16:31]
	v_mfma_f32_32x32x16_bf16 v[48:63], v[150:153], v[128:131], v[48:63]
	v_mfma_f32_32x32x16_bf16 v[80:95], v[150:153], v[140:143], v[80:95]
	v_mfma_f32_32x32x16_bf16 v[112:127], v[150:153], v[146:149], v[112:127]
	ds_read_b128 v[150:153], v194 offset:36864
	v_mfma_f32_32x32x16_bf16 v[0:15], v[162:165], v[136:139], v[0:15]
	ds_read_b128 v[136:139], v195 offset:4096
	v_mfma_f32_32x32x16_bf16 v[32:47], v[162:165], v[128:131], v[32:47]
	ds_read_b128 v[128:131], v194 offset:32768
	v_mfma_f32_32x32x16_bf16 v[64:79], v[162:165], v[140:143], v[64:79]
	ds_read_b128 v[140:143], v195 offset:8192
	v_mfma_f32_32x32x16_bf16 v[96:111], v[162:165], v[146:149], v[96:111]
	ds_read_b128 v[146:149], v195 offset:12288
	s_cmp_lt_u32 s45, 15
	s_mov_b64 s[6:7], -1
	s_cbranch_scc1 .Lft_L1_728
	s_add_i32 s50, s46, 0x10000
	s_mov_b64 s[6:7], 0

.Lxt_L1:
	v_mfma_f32_32x32x16_bf16 v[0:15], v[162:165], v[136:139], v[0:15]
	v_mfma_f32_32x32x16_bf16 v[16:31], v[150:153], v[136:139], v[16:31]
	v_mfma_f32_32x32x16_bf16 v[32:47], v[162:165], v[128:131], v[32:47]
	v_mfma_f32_32x32x16_bf16 v[48:63], v[150:153], v[128:131], v[48:63]
	v_mfma_f32_32x32x16_bf16 v[64:79], v[162:165], v[140:143], v[64:79]
	v_mfma_f32_32x32x16_bf16 v[80:95], v[150:153], v[140:143], v[80:95]
	v_mfma_f32_32x32x16_bf16 v[96:111], v[162:165], v[146:149], v[96:111]
	v_mfma_f32_32x32x16_bf16 v[112:127], v[150:153], v[146:149], v[112:127]
	s_branch .LBB0_730

.Lkin_L1:
	s_and_b32 s6, s46, 0x10000
	v_or_b32_e32 v144, s6, v187
	v_add_u32_e32 v194, v144, v188
	v_add_u32_e32 v166, s6, v186
	v_add_u32_e32 v195, v166, v188
	ds_read_b128 v[132:135], v195
	ds_read_b128 v[150:153], v194 offset:36864
	ds_read_b128 v[136:139], v195 offset:4096
	ds_read_b128 v[128:131], v194 offset:32768
	ds_read_b128 v[140:143], v195 offset:8192
	ds_read_b128 v[146:149], v195 offset:12288
	s_cmp_lt_u32 s45, 15
	s_mov_b64 s[6:7], -1
	s_cbranch_scc1 .LBB0_728
	s_add_i32 s50, s46, 0x10000
	s_mov_b64 s[6:7], 0
